# diff unit prologue: two 32-gain max scans as one lane-parallel load each + wave max instead of 4 serialized load/wait groups
# baseline (speedup 1.0000x reference)
.LBB0_1743:
	v_readlane_b32 s0, v254, 26
	v_readlane_b32 s2, v254, 63
	v_readlane_b32 s3, v255, 0
	v_mov_b32_e32 v0, s0
	ds_read2_b32 v[2:3], v0 offset1:1
	s_waitcnt lgkmcnt(0)
	v_readfirstlane_b32 s0, v2
	v_readfirstlane_b32 s1, v3
	s_add_u32 s0, s0, s2
	s_addc_u32 s1, s1, s3
	s_nop 2
	v_mbcnt_lo_u32_b32 v4, -1, 0
	v_mbcnt_hi_u32_b32 v4, -1, v4
	v_and_b32_e32 v4, 31, v4
	v_lshlrev_b32_e32 v4, 2, v4
	global_load_dword v5, v4, s[0:1]
	s_mov_b32 s0, s55
	v_mov_b32_e32 v2, s0
	ds_read2_b32 v[2:3], v2 offset1:1
	s_waitcnt lgkmcnt(0)
	v_readfirstlane_b32 s0, v2
	v_readfirstlane_b32 s1, v3
	s_add_u32 s0, s0, s2
	s_addc_u32 s1, s1, s3
	s_nop 4
	global_load_dword v6, v4, s[0:1]
	s_ashr_i32 s2, s91, 2
	s_mul_hi_i32 s10, s2, 0x2c00000
	s_mul_i32 s11, s2, 0x2c00000
	s_mov_b32 s0, 0x42700000
	s_waitcnt vmcnt(0)
	v_max_f32_e64 v0, |v5|, |v5|
	v_max_f32_e64 v2, |v6|, |v6|
	v_mov_b32_e32 v5, v0
	v_mov_b32_e32 v6, v2
	s_nop 1
	v_permlane16_swap_b32_e32 v5, v0
	v_permlane16_swap_b32_e32 v6, v2
	v_max_f32_e32 v0, v0, v5
	v_max_f32_e32 v2, v2, v6
	s_nop 1
	v_max_f32_dpp v0, v0, v0 row_ror:8 row_mask:0xf bank_mask:0xf
	v_max_f32_dpp v2, v2, v2 row_ror:8 row_mask:0xf bank_mask:0xf
	s_nop 1
	v_max_f32_dpp v0, v0, v0 row_ror:4 row_mask:0xf bank_mask:0xf
	v_max_f32_dpp v2, v2, v2 row_ror:4 row_mask:0xf bank_mask:0xf
	s_nop 1
	v_max_f32_dpp v0, v0, v0 row_ror:2 row_mask:0xf bank_mask:0xf
	v_max_f32_dpp v2, v2, v2 row_ror:2 row_mask:0xf bank_mask:0xf
	s_nop 1
	v_max_f32_dpp v0, v0, v0 row_ror:1 row_mask:0xf bank_mask:0xf
	v_max_f32_dpp v2, v2, v2 row_ror:1 row_mask:0xf bank_mask:0xf
	s_nop 1
	v_mul_f32_e32 v0, 0x4103e235, v0
	v_mul_f32_e32 v0, v0, v2
	v_cmp_nlt_f32_e32 vcc, s0, v0
	s_mov_b64 s[0:1], -1
	s_cbranch_vccz .LBB0_1755
	s_mov_b32 s0, s33
	s_mov_b32 s3, s33
	v_mov_b32_e32 v0, s0
	ds_read2_b32 v[2:3], v0 offset1:1
	s_mov_b32 s0, s33
	v_mov_b32_e32 v159, v1
	v_mov_b32_e32 v0, s3
	s_waitcnt lgkmcnt(0)
	v_readfirstlane_b32 s0, v2
	v_readfirstlane_b32 s1, v3
	ds_read2_b32 v[2:3], v0 offset1:1
	v_mov_b32_e32 v0, v1
	s_add_u32 s0, s0, 0xaa00000
	s_getreg_b32 s3, hwreg(HW_REG_HW_ID, 0, 6)
	s_addc_u32 s1, s1, 0
	s_lshl_b32 s3, s3, 2
	s_and_b32 s3, s3, 0xfc
	v_add_u32_e32 v4, s3, v0
	v_add_u32_e32 v4, 0x24800, v4
	ds_read_b32 v4, v4
	v_mbcnt_lo_u32_b32 v0, -1, v0
	v_mbcnt_hi_u32_b32 v6, -1, v0
	s_lshl_b32 s6, s86, 8
	v_and_b32_e32 v8, 31, v6
	s_waitcnt lgkmcnt(0)
	v_readfirstlane_b32 s3, v4
	v_mov_b64_e32 v[4:5], s[0:1]
	v_bfe_u32 v9, v6, 5, 1
	v_lshl_add_u32 v7, s3, 6, v6
	v_ashrrev_i32_e32 v0, 1, v7
	v_and_b32_e32 v0, 0xffffffe0, v0
	v_add_u32_e32 v172, s6, v0
	s_ashr_i32 s3, s2, 31
	v_or_b32_e32 v156, v172, v8
	s_lshl_b64 s[4:5], s[2:3], 13
	v_ashrrev_i32_e32 v157, 31, v156
	v_lshl_add_u64 v[154:155], s[4:5], 0, v[156:157]
	s_lshl_b32 s3, s91, 6
	v_mad_u64_u32 v[4:5], s[4:5], v154, s89, v[4:5]
	s_and_b32 s3, s3, 0xc0
	s_add_i32 s4, s6, 0x100
	s_lshl_b32 s94, s3, 1
	s_lshr_b32 s4, s4, 6
	s_add_u32 s0, s0, s11
	s_addc_u32 s1, s1, s10
	s_add_u32 s0, s0, s94
	s_addc_u32 s1, s1, 0
	s_add_i32 s12, s4, -1
	v_mad_i32_i24 v5, v155, s89, v5
	s_mul_i32 s4, s12, 0x58000
	v_lshl_add_u64 v[4:5], v[4:5], 0, s[94:95]
	v_lshlrev_b32_e32 v0, 4, v9
	s_mul_hi_u32 s5, s12, 0x58000
	s_add_u32 s4, s0, s4
	v_lshl_add_u64 v[4:5], v[4:5], 0, v[0:1]
	s_addc_u32 s5, s1, s5
	global_load_dwordx4 v[130:133], v[4:5], off
	global_load_dwordx4 v[134:137], v[4:5], off offset:32
	global_load_dwordx4 v[138:141], v[4:5], off offset:64
	global_load_dwordx4 v[142:145], v[4:5], off offset:96
	v_ashrrev_i32_e32 v7, 3, v7
	v_mov_b64_e32 v[4:5], s[4:5]
	v_lshlrev_b32_e32 v10, 4, v6
	v_mad_i64_i32 v[4:5], s[4:5], v7, s89, v[4:5]
	v_and_b32_e32 v158, 0x70, v10
	v_lshl_add_u64 v[4:5], v[4:5], 0, v[158:159]
	global_load_dwordx4 v[146:149], v[4:5], off offset:512
	global_load_dwordx4 v[150:153], v[4:5], off offset:1024
	v_readfirstlane_b32 s4, v2
	v_readfirstlane_b32 s5, v3
	v_mov_b64_e32 v[2:3], s[0:1]
	v_mad_i64_i32 v[2:3], s[0:1], v7, s89, v[2:3]
	v_lshl_add_u64 v[160:161], v[2:3], 0, v[158:159]
	v_bfe_u32 v3, v6, 2, 2
	v_lshrrev_b32_e32 v4, 3, v6
	v_and_or_b32 v3, v4, 4, v3
	v_and_b32_e32 v2, 16, v6
	v_mul_u32_u24_e32 v187, 0x90, v3
	v_lshlrev_b32_e32 v3, 2, v6
	v_and_or_b32 v2, v3, 12, v2
	v_mov_b32_e32 v16, v1
	v_mov_b32_e32 v17, v1
	v_mul_lo_u32 v173, v7, s66
	v_mul_u32_u24_e32 v186, 0x90, v8
	v_lshlrev_b32_e32 v157, 2, v9
	v_lshlrev_b32_e32 v188, 1, v2
	v_mov_b32_e32 v2, v1
	v_mov_b32_e32 v3, v1
	v_mov_b32_e32 v4, v1
	v_mov_b32_e32 v5, v1
	v_mov_b32_e32 v6, v1
	v_mov_b32_e32 v7, v1
	v_mov_b32_e32 v8, v1
	v_mov_b32_e32 v9, v1
	v_mov_b32_e32 v10, v1
	v_mov_b32_e32 v11, v1
	v_mov_b32_e32 v12, v1
	v_mov_b32_e32 v13, v1
	v_mov_b32_e32 v14, v1
	v_mov_b32_e32 v15, v1
	v_mov_b64_e32 v[32:33], v[16:17]
	v_mov_b64_e32 v[48:49], v[16:17]
	v_mov_b64_e32 v[64:65], v[16:17]
	s_mov_b32 s13, 0
	v_or_b32_e32 v174, 31, v172
	s_or_b32 s14, s6, 0xff
	v_mov_b32_e32 v159, 0
	v_mov_b64_e32 v[30:31], v[14:15]
	v_mov_b64_e32 v[28:29], v[12:13]
	v_mov_b64_e32 v[26:27], v[10:11]
	v_mov_b64_e32 v[24:25], v[8:9]
	v_mov_b64_e32 v[22:23], v[6:7]
	v_mov_b64_e32 v[20:21], v[4:5]
	v_mov_b64_e32 v[18:19], v[2:3]
	v_mov_b64_e32 v[46:47], v[14:15]
	v_mov_b64_e32 v[44:45], v[12:13]
	v_mov_b64_e32 v[42:43], v[10:11]
	v_mov_b64_e32 v[40:41], v[8:9]
	v_mov_b64_e32 v[38:39], v[6:7]
	v_mov_b64_e32 v[36:37], v[4:5]
	v_mov_b64_e32 v[34:35], v[2:3]
	v_mov_b64_e32 v[62:63], v[14:15]
	v_mov_b64_e32 v[60:61], v[12:13]
	v_mov_b64_e32 v[58:59], v[10:11]
	v_mov_b64_e32 v[56:57], v[8:9]
	v_mov_b64_e32 v[54:55], v[6:7]
	v_mov_b64_e32 v[52:53], v[4:5]
	v_mov_b64_e32 v[50:51], v[2:3]
	v_mov_b32_e32 v189, 0
	s_branch .LBB0_1747
